# retention unit epilogue: all 16 sg/gn load pairs issued up front, counted vmcnt per round (was 16 load-drain-store round trips)
# speedup vs baseline: 1.0138x; 1.0026x over previous
.LBB0_150:
	s_and_b64 vcc, exec, s[4:5]
	s_cbranch_vccz .LBB0_14
	s_add_u32 s12, s10, 0x80000
	s_addc_u32 s13, s11, 0
	s_add_u32 s14, s10, 0x15100000
	v_writelane_b32 v254, s15, 63
	s_addc_u32 s15, s11, 0
	s_mov_b64 s[18:19], -1
	s_mov_b64 s[4:5], 0
	s_cmp_lt_i32 s28, 15
	s_mov_b64 s[16:17], 0
	s_cbranch_scc1 .LBB0_159
	s_cmp_eq_u32 s28, 15
	s_mov_b64 s[16:17], -1
	s_cbranch_scc0 .LBB0_157
	v_lshl_add_u32 v0, s90, 9, v170
	s_mov_b32 s6, 0x400000
	v_cmp_gt_i32_e32 vcc, s6, v0
	s_and_saveexec_b64 s[16:17], vcc
	s_cbranch_execz .LBB0_156
	s_add_u32 s18, s10, 0x60000
	s_addc_u32 s19, s11, 0
	s_lshl_b32 s20, s89, 9
	v_and_b32_e32 v1, 0x1ff, v170
	v_readlane_b32 s36, v253, 0
	v_lshlrev_b32_e32 v8, 4, v1
	v_readlane_b32 s38, v253, 2
	v_readlane_b32 s39, v253, 3
	v_readlane_b32 s40, v253, 4
	v_readlane_b32 s41, v253, 5
	v_ashrrev_i32_e32 v1, 31, v0
	s_ashr_i32 s21, s20, 31
	v_lshl_add_u64 v[2:3], s[38:39], 0, v[8:9]
	v_lshl_add_u64 v[4:5], v[0:1], 4, s[40:41]
	s_lshl_b64 s[26:27], s[20:21], 4
	v_lshl_add_u64 v[6:7], v[0:1], 3, s[14:15]
	s_lshl_b64 s[28:29], s[20:21], 3
	s_mov_b64 s[30:31], 0
	v_readlane_b32 s37, v253, 1
	v_readlane_b32 s42, v253, 6
	v_readlane_b32 s43, v253, 7
	global_load_dwordx4 v[20:23], v[2:3], off
.LBB0_155:
	v_ashrrev_i32_e32 v10, 9, v0
	v_ashrrev_i32_e32 v11, 31, v10
	v_lshl_add_u64 v[10:11], v[10:11], 3, s[18:19]
	global_load_dwordx2 v[14:15], v[10:11], off
	global_load_dwordx2 v[16:17], v[6:7], off
	v_add_u32_e32 v24, s20, v0
	v_cmp_gt_i32_e32 vcc, 0x400000, v24
	s_and_saveexec_b64 s[36:37], vcc
	s_mov_b64 s[38:39], exec
	v_ashrrev_i32_e32 v10, 9, v24
	v_ashrrev_i32_e32 v11, 31, v10
	v_lshl_add_u64 v[10:11], v[10:11], 3, s[18:19]
	v_lshl_add_u64 v[30:31], v[6:7], 0, s[28:29]
	global_load_dwordx2 v[26:27], v[10:11], off
	global_load_dwordx2 v[28:29], v[30:31], off
	s_mov_b64 exec, s[36:37]
	s_min_u32 s6, s85, 32
	s_sub_i32 s8, 32, s6
	s_waitcnt vmcnt(0)
	v_mov_b32_e32 v8, v15
	v_cvt_f32_u32_e32 v1, v14
	v_lshlrev_b64 v[14:15], s6, v[8:9]
	v_min_u32_e32 v8, 1, v14
	v_or_b32_e32 v8, v15, v8
	v_cvt_f32_u32_e32 v8, v8
	v_lshlrev_b32_e32 v18, 16, v16
	v_and_b32_e32 v19, 0xffff0000, v16
	v_lshlrev_b32_e32 v16, 16, v17
	v_ldexp_f32 v8, v8, s8
	v_fmac_f32_e32 v8, 0x2f800000, v1
	v_fmamk_f32 v1, v8, 0x3a000000, v183
	v_rsq_f32_e32 v8, v1
	v_and_b32_e32 v17, 0xffff0000, v17
	v_pk_mul_f32 v[14:15], v[8:9], v[18:19] op_sel_hi:[0,1]
	v_pk_mul_f32 v[16:17], v[8:9], v[16:17] op_sel_hi:[0,1]
	v_pk_mul_f32 v[12:13], v[22:23], v[16:17]
	v_pk_mul_f32 v[10:11], v[20:21], v[14:15]
	global_store_dwordx4 v[4:5], v[10:13], off nt
	v_mov_b32_e32 v8, v27
	v_cvt_f32_u32_e32 v1, v26
	v_lshlrev_b64 v[26:27], s6, v[8:9]
	v_min_u32_e32 v8, 1, v26
	v_or_b32_e32 v8, v27, v8
	v_cvt_f32_u32_e32 v8, v8
	v_lshlrev_b32_e32 v18, 16, v28
	v_and_b32_e32 v19, 0xffff0000, v28
	v_lshlrev_b32_e32 v28, 16, v29
	v_ldexp_f32 v8, v8, s8
	v_fmac_f32_e32 v8, 0x2f800000, v1
	v_fmamk_f32 v1, v8, 0x3a000000, v183
	v_rsq_f32_e32 v8, v1
	v_and_b32_e32 v29, 0xffff0000, v29
	v_pk_mul_f32 v[26:27], v[8:9], v[18:19] op_sel_hi:[0,1]
	v_pk_mul_f32 v[28:29], v[8:9], v[28:29] op_sel_hi:[0,1]
	v_pk_mul_f32 v[34:35], v[22:23], v[28:29]
	v_pk_mul_f32 v[32:33], v[20:21], v[26:27]
	v_lshl_add_u64 v[30:31], v[4:5], 0, s[26:27]
	s_mov_b64 exec, s[38:39]
	global_store_dwordx4 v[30:31], v[32:35], off nt
	s_mov_b64 exec, s[36:37]
	v_add_u32_e32 v0, s20, v24
	v_lshl_add_u64 v[6:7], s[28:29], 1, v[6:7]
	v_lshl_add_u64 v[4:5], s[26:27], 1, v[4:5]
	v_cmp_lt_i32_e32 vcc, 0x3fffff, v0
	s_or_b64 s[30:31], vcc, s[30:31]
	s_andn2_b64 exec, exec, s[30:31]
	s_cbranch_execnz .LBB0_155

.LBB0_861:
	s_nop 2
	v_pk_mul_f32 v[0:1], v[72:73], v[72:73]
	v_pk_mul_f32 v[2:3], v[70:71], v[70:71]
	v_mov_b32_e32 v8, v170
	v_pk_mov_b32 v[4:5], v[2:3], v[0:1] op_sel:[1,0]
	v_mov_b32_e32 v3, v1
	v_pk_add_f32 v[0:1], v[4:5], v[2:3]
	v_pk_mul_f32 v[2:3], v[68:69], v[68:69]
	v_pk_add_f32 v[0:1], v[0:1], v[0:1] op_sel_hi:[0,1]
	v_pk_mul_f32 v[4:5], v[66:67], v[66:67]
	v_mul_f32_e32 v0, v62, v62
	v_pk_mov_b32 v[6:7], v[4:5], v[2:3] op_sel:[1,0]
	v_mov_b32_e32 v5, v3
	v_pk_add_f32 v[2:3], v[6:7], v[4:5]
	v_pk_fma_f32 v[4:5], v[62:63], v[62:63], v[0:1] op_sel_hi:[1,1,0]
	v_mul_f32_e32 v0, v64, v64
	v_pk_add_f32 v[2:3], v[2:3], v[2:3] op_sel_hi:[0,1]
	v_pk_fma_f32 v[6:7], v[64:65], v[64:65], v[0:1] op_sel_hi:[1,1,0]
	v_mul_f32_e32 v4, v58, v58
	v_mul_f32_e32 v6, v59, v59
	v_mul_f32_e32 v2, v60, v60
	v_mul_f32_e32 v0, v61, v61
	v_pk_add_f32 v[4:5], v[4:5], v[6:7]
	v_pk_add_f32 v[0:1], v[2:3], v[0:1]
	v_pk_mul_f32 v[2:3], v[56:57], v[56:57]
	v_pk_add_f32 v[0:1], v[4:5], v[0:1]
	v_pk_mul_f32 v[4:5], v[54:55], v[54:55]
	v_pk_add_f32 v[0:1], v[0:1], v[0:1] op_sel_hi:[0,1]
	v_pk_mov_b32 v[6:7], v[4:5], v[2:3] op_sel:[1,0]
	v_mov_b32_e32 v5, v3
	v_mul_f32_e32 v0, v50, v50
	v_pk_add_f32 v[2:3], v[6:7], v[4:5]
	v_pk_fma_f32 v[4:5], v[50:51], v[50:51], v[0:1] op_sel_hi:[1,1,0]
	v_mul_f32_e32 v0, v52, v52
	v_pk_add_f32 v[2:3], v[2:3], v[2:3] op_sel_hi:[0,1]
	v_pk_fma_f32 v[6:7], v[52:53], v[52:53], v[0:1] op_sel_hi:[1,1,0]
	v_mul_f32_e32 v4, v46, v46
	v_mul_f32_e32 v6, v47, v47
	v_mul_f32_e32 v2, v48, v48
	v_mul_f32_e32 v0, v49, v49
	v_pk_add_f32 v[4:5], v[4:5], v[6:7]
	v_pk_add_f32 v[0:1], v[2:3], v[0:1]
	v_pk_mul_f32 v[2:3], v[44:45], v[44:45]
	v_pk_add_f32 v[0:1], v[4:5], v[0:1]
	v_pk_mul_f32 v[4:5], v[42:43], v[42:43]
	v_pk_add_f32 v[0:1], v[0:1], v[0:1] op_sel_hi:[0,1]
	v_pk_mov_b32 v[6:7], v[4:5], v[2:3] op_sel:[1,0]
	v_mov_b32_e32 v5, v3
	v_mul_f32_e32 v0, v38, v38
	v_pk_add_f32 v[2:3], v[6:7], v[4:5]
	v_pk_fma_f32 v[4:5], v[38:39], v[38:39], v[0:1] op_sel_hi:[1,1,0]
	v_mul_f32_e32 v0, v40, v40
	v_pk_add_f32 v[2:3], v[2:3], v[2:3] op_sel_hi:[0,1]
	v_pk_fma_f32 v[6:7], v[40:41], v[40:41], v[0:1] op_sel_hi:[1,1,0]
	v_mul_f32_e32 v4, v34, v34
	v_mul_f32_e32 v6, v35, v35
	v_mul_f32_e32 v2, v36, v36
	v_mul_f32_e32 v0, v37, v37
	v_pk_add_f32 v[4:5], v[4:5], v[6:7]
	v_pk_add_f32 v[0:1], v[2:3], v[0:1]
	v_pk_mul_f32 v[2:3], v[32:33], v[32:33]
	v_pk_add_f32 v[0:1], v[4:5], v[0:1]
	v_pk_mul_f32 v[4:5], v[30:31], v[30:31]
	v_pk_add_f32 v[0:1], v[0:1], v[0:1] op_sel_hi:[0,1]
	v_pk_mov_b32 v[6:7], v[4:5], v[2:3] op_sel:[1,0]
	v_mov_b32_e32 v5, v3
	v_mul_f32_e32 v0, v26, v26
	v_pk_add_f32 v[2:3], v[6:7], v[4:5]
	v_pk_fma_f32 v[4:5], v[26:27], v[26:27], v[0:1] op_sel_hi:[1,1,0]
	v_mul_f32_e32 v0, v28, v28
	v_pk_add_f32 v[2:3], v[2:3], v[2:3] op_sel_hi:[0,1]
	v_pk_fma_f32 v[6:7], v[28:29], v[28:29], v[0:1] op_sel_hi:[1,1,0]
	v_mul_f32_e32 v4, v22, v22
	v_mul_f32_e32 v6, v23, v23
	v_mul_f32_e32 v2, v24, v24
	v_mul_f32_e32 v0, v25, v25
	v_pk_add_f32 v[4:5], v[4:5], v[6:7]
	v_pk_add_f32 v[0:1], v[2:3], v[0:1]
	v_pk_mul_f32 v[2:3], v[20:21], v[20:21]
	v_pk_add_f32 v[0:1], v[4:5], v[0:1]
	v_pk_mul_f32 v[4:5], v[18:19], v[18:19]
	v_pk_add_f32 v[0:1], v[0:1], v[0:1] op_sel_hi:[0,1]
	v_pk_mov_b32 v[6:7], v[4:5], v[2:3] op_sel:[1,0]
	v_mov_b32_e32 v5, v3
	v_pk_add_f32 v[2:3], v[6:7], v[4:5]
	v_mul_f32_e32 v0, v14, v14
	v_pk_add_f32 v[2:3], v[2:3], v[2:3] op_sel_hi:[0,1]
	v_pk_fma_f32 v[4:5], v[14:15], v[14:15], v[0:1] op_sel_hi:[1,1,0]
	v_mul_f32_e32 v0, v16, v16
	v_pk_fma_f32 v[6:7], v[16:17], v[16:17], v[0:1] op_sel_hi:[1,1,0]
	v_mul_f32_e32 v2, v12, v12
	v_mul_f32_e32 v0, v13, v13
	v_pk_add_f32 v[0:1], v[2:3], v[0:1]
	v_and_b32_e32 v3, 64, v184
	v_mul_f32_e32 v4, v10, v10
	v_mul_f32_e32 v6, v11, v11
	v_xor_b32_e32 v2, 16, v184
	v_add_u32_e32 v3, 64, v3
	v_pk_add_f32 v[4:5], v[4:5], v[6:7]
	v_cmp_lt_i32_e32 vcc, v2, v3
	v_pk_add_f32 v[0:1], v[4:5], v[0:1]
	s_nop 0
	v_cndmask_b32_e32 v2, v184, v2, vcc
	v_add_f32_e32 v1, v0, v1
	v_lshlrev_b32_e32 v2, 2, v2
	ds_bpermute_b32 v2, v2, v1
	s_barrier
	s_waitcnt lgkmcnt(0)
	s_mov_b64 s[4:5], 0
	v_add_f32_e32 v1, v1, v2
	v_xor_b32_e32 v2, 32, v184
	v_cmp_lt_i32_e32 vcc, v2, v3
	v_ashrrev_i32_e32 v74, 2, v8
	v_and_or_b32 v75, v8, 15, s9
	v_cndmask_b32_e32 v2, v184, v2, vcc
	v_lshlrev_b32_e32 v2, 2, v2
	ds_bpermute_b32 v2, v2, v1
	v_and_b32_e32 v0, -16, v74
	v_add_u32_e32 v0, v75, v0
	v_lshrrev_b32_e32 v5, 2, v8
	v_and_b32_e32 v5, 12, v5
	s_waitcnt lgkmcnt(0)
	v_add_f32_e32 v1, v1, v2
	v_fmamk_f32 v1, v1, 0x3b800000, v183
	v_rsq_f32_e32 v4, v1
	v_ashrrev_i32_e32 v1, 31, v0
	v_lshlrev_b64 v[2:3], 12, v[0:1]
	v_lshlrev_b64 v[0:1], 14, v[0:1]
	v_lshlrev_b32_e32 v8, 1, v5
	v_lshl_add_u64 v[0:1], s[30:31], 0, v[0:1]
	v_lshl_add_u64 v[2:3], s[28:29], 0, v[2:3]
	v_lshl_add_u64 v[74:75], v[0:1], 0, v[8:9]
	v_lshl_add_u64 v[6:7], v[2:3], 0, v[8:9]
	v_lshlrev_b32_e32 v5, 2, v5
	global_load_dwordx2 v[142:143], v[74:75], off
	global_load_dwordx4 v[78:81], v5, s[34:35]
	global_load_dwordx2 v[144:145], v[74:75], off offset:32
	global_load_dwordx4 v[82:85], v5, s[34:35] offset:64
	global_load_dwordx2 v[146:147], v[74:75], off offset:64
	global_load_dwordx4 v[86:89], v5, s[34:35] offset:128
	global_load_dwordx2 v[148:149], v[74:75], off offset:96
	global_load_dwordx4 v[90:93], v5, s[34:35] offset:192
	global_load_dwordx2 v[150:151], v[74:75], off offset:128
	global_load_dwordx4 v[94:97], v5, s[34:35] offset:256
	global_load_dwordx2 v[152:153], v[74:75], off offset:160
	global_load_dwordx4 v[98:101], v5, s[34:35] offset:320
	global_load_dwordx2 v[198:199], v[74:75], off offset:192
	global_load_dwordx4 v[102:105], v5, s[34:35] offset:384
	global_load_dwordx2 v[200:201], v[74:75], off offset:224
	global_load_dwordx4 v[106:109], v5, s[34:35] offset:448
	global_load_dwordx2 v[202:203], v[74:75], off offset:256
	global_load_dwordx4 v[110:113], v5, s[34:35] offset:512
	global_load_dwordx2 v[204:205], v[74:75], off offset:288
	global_load_dwordx4 v[114:117], v5, s[34:35] offset:576
	global_load_dwordx2 v[206:207], v[74:75], off offset:320
	global_load_dwordx4 v[118:121], v5, s[34:35] offset:640
	global_load_dwordx2 v[208:209], v[74:75], off offset:352
	global_load_dwordx4 v[122:125], v5, s[34:35] offset:704
	global_load_dwordx2 v[210:211], v[74:75], off offset:384
	global_load_dwordx4 v[126:129], v5, s[34:35] offset:768
	global_load_dwordx2 v[212:213], v[74:75], off offset:416
	global_load_dwordx4 v[130:133], v5, s[34:35] offset:832
	global_load_dwordx2 v[214:215], v[74:75], off offset:448
	global_load_dwordx4 v[134:137], v5, s[34:35] offset:896
	global_load_dwordx2 v[216:217], v[74:75], off offset:480
	global_load_dwordx4 v[138:141], v5, s[34:35] offset:960
	v_pk_mul_f32 v[70:71], v[70:71], v[4:5] op_sel_hi:[1,0]
	v_pk_mul_f32 v[66:67], v[66:67], v[4:5] op_sel_hi:[1,0]
	v_pk_mul_f32 v[62:63], v[62:63], v[4:5] op_sel_hi:[1,0]
	v_pk_mul_f32 v[58:59], v[58:59], v[4:5] op_sel_hi:[1,0]
	v_pk_mul_f32 v[54:55], v[54:55], v[4:5] op_sel_hi:[1,0]
	v_pk_mul_f32 v[50:51], v[50:51], v[4:5] op_sel_hi:[1,0]
	v_pk_mul_f32 v[46:47], v[46:47], v[4:5] op_sel_hi:[1,0]
	v_pk_mul_f32 v[42:43], v[42:43], v[4:5] op_sel_hi:[1,0]
	v_pk_mul_f32 v[38:39], v[38:39], v[4:5] op_sel_hi:[1,0]
	v_pk_mul_f32 v[34:35], v[34:35], v[4:5] op_sel_hi:[1,0]
	v_pk_mul_f32 v[30:31], v[30:31], v[4:5] op_sel_hi:[1,0]
	v_pk_mul_f32 v[26:27], v[26:27], v[4:5] op_sel_hi:[1,0]
	v_pk_mul_f32 v[22:23], v[22:23], v[4:5] op_sel_hi:[1,0]
	v_pk_mul_f32 v[18:19], v[18:19], v[4:5] op_sel_hi:[1,0]
	v_pk_mul_f32 v[14:15], v[14:15], v[4:5] op_sel_hi:[1,0]
	v_pk_mul_f32 v[10:11], v[10:11], v[4:5] op_sel_hi:[1,0]
	s_and_b64 vcc, exec, s[46:47]
	s_waitcnt vmcnt(30)
	v_pk_mul_f32 v[0:1], v[78:79], v[70:71]
	v_lshlrev_b32_e32 v2, 16, v142
	v_and_b32_e32 v3, 0xffff0000, v142
	v_pk_mul_f32 v[0:1], v[0:1], v[2:3]
	v_pk_mul_f32 v[2:3], v[72:73], v[4:5] op_sel_hi:[1,0]
	v_pk_mul_f32 v[2:3], v[80:81], v[2:3]
	v_lshlrev_b32_e32 v76, 16, v143
	v_and_b32_e32 v77, 0xffff0000, v143
	v_pk_mul_f32 v[2:3], v[2:3], v[76:77]
	v_cvt_pk_bf16_f32 v0, v0, v1
	v_cvt_pk_bf16_f32 v1, v2, v3
	global_store_dwordx2 v[6:7], v[0:1], off
	s_waitcnt vmcnt(29)
	v_pk_mul_f32 v[0:1], v[82:83], v[66:67]
	v_lshlrev_b32_e32 v2, 16, v144
	v_and_b32_e32 v3, 0xffff0000, v144
	v_pk_mul_f32 v[0:1], v[0:1], v[2:3]
	v_pk_mul_f32 v[2:3], v[68:69], v[4:5] op_sel_hi:[1,0]
	v_pk_mul_f32 v[2:3], v[84:85], v[2:3]
	v_lshlrev_b32_e32 v76, 16, v145
	v_and_b32_e32 v77, 0xffff0000, v145
	v_pk_mul_f32 v[2:3], v[2:3], v[76:77]
	v_cvt_pk_bf16_f32 v0, v0, v1
	v_cvt_pk_bf16_f32 v1, v2, v3
	global_store_dwordx2 v[6:7], v[0:1], off offset:32
	s_waitcnt vmcnt(28)
	v_pk_mul_f32 v[0:1], v[86:87], v[62:63]
	v_lshlrev_b32_e32 v2, 16, v146
	v_and_b32_e32 v3, 0xffff0000, v146
	v_pk_mul_f32 v[0:1], v[0:1], v[2:3]
	v_pk_mul_f32 v[2:3], v[64:65], v[4:5] op_sel_hi:[1,0]
	v_pk_mul_f32 v[2:3], v[88:89], v[2:3]
	v_lshlrev_b32_e32 v76, 16, v147
	v_and_b32_e32 v77, 0xffff0000, v147
	v_pk_mul_f32 v[2:3], v[2:3], v[76:77]
	v_cvt_pk_bf16_f32 v0, v0, v1
	v_cvt_pk_bf16_f32 v1, v2, v3
	global_store_dwordx2 v[6:7], v[0:1], off offset:64
	s_waitcnt vmcnt(27)
	v_pk_mul_f32 v[0:1], v[90:91], v[58:59]
	v_lshlrev_b32_e32 v2, 16, v148
	v_and_b32_e32 v3, 0xffff0000, v148
	v_pk_mul_f32 v[0:1], v[0:1], v[2:3]
	v_pk_mul_f32 v[2:3], v[60:61], v[4:5] op_sel_hi:[1,0]
	v_pk_mul_f32 v[2:3], v[92:93], v[2:3]
	v_lshlrev_b32_e32 v76, 16, v149
	v_and_b32_e32 v77, 0xffff0000, v149
	v_pk_mul_f32 v[2:3], v[2:3], v[76:77]
	v_cvt_pk_bf16_f32 v0, v0, v1
	v_cvt_pk_bf16_f32 v1, v2, v3
	global_store_dwordx2 v[6:7], v[0:1], off offset:96
	s_waitcnt vmcnt(26)
	v_pk_mul_f32 v[0:1], v[94:95], v[54:55]
	v_lshlrev_b32_e32 v2, 16, v150
	v_and_b32_e32 v3, 0xffff0000, v150
	v_pk_mul_f32 v[0:1], v[0:1], v[2:3]
	v_pk_mul_f32 v[2:3], v[56:57], v[4:5] op_sel_hi:[1,0]
	v_pk_mul_f32 v[2:3], v[96:97], v[2:3]
	v_lshlrev_b32_e32 v76, 16, v151
	v_and_b32_e32 v77, 0xffff0000, v151
	v_pk_mul_f32 v[2:3], v[2:3], v[76:77]
	v_cvt_pk_bf16_f32 v0, v0, v1
	v_cvt_pk_bf16_f32 v1, v2, v3
	global_store_dwordx2 v[6:7], v[0:1], off offset:128
	s_waitcnt vmcnt(25)
	v_pk_mul_f32 v[0:1], v[98:99], v[50:51]
	v_lshlrev_b32_e32 v2, 16, v152
	v_and_b32_e32 v3, 0xffff0000, v152
	v_pk_mul_f32 v[0:1], v[0:1], v[2:3]
	v_pk_mul_f32 v[2:3], v[52:53], v[4:5] op_sel_hi:[1,0]
	v_pk_mul_f32 v[2:3], v[100:101], v[2:3]
	v_lshlrev_b32_e32 v76, 16, v153
	v_and_b32_e32 v77, 0xffff0000, v153
	v_pk_mul_f32 v[2:3], v[2:3], v[76:77]
	v_cvt_pk_bf16_f32 v0, v0, v1
	v_cvt_pk_bf16_f32 v1, v2, v3
	global_store_dwordx2 v[6:7], v[0:1], off offset:160
	s_waitcnt vmcnt(24)
	v_pk_mul_f32 v[0:1], v[102:103], v[46:47]
	v_lshlrev_b32_e32 v2, 16, v198
	v_and_b32_e32 v3, 0xffff0000, v198
	v_pk_mul_f32 v[0:1], v[0:1], v[2:3]
	v_pk_mul_f32 v[2:3], v[48:49], v[4:5] op_sel_hi:[1,0]
	v_pk_mul_f32 v[2:3], v[104:105], v[2:3]
	v_lshlrev_b32_e32 v76, 16, v199
	v_and_b32_e32 v77, 0xffff0000, v199
	v_pk_mul_f32 v[2:3], v[2:3], v[76:77]
	v_cvt_pk_bf16_f32 v0, v0, v1
	v_cvt_pk_bf16_f32 v1, v2, v3
	global_store_dwordx2 v[6:7], v[0:1], off offset:192
	s_waitcnt vmcnt(23)
	v_pk_mul_f32 v[0:1], v[106:107], v[42:43]
	v_lshlrev_b32_e32 v2, 16, v200
	v_and_b32_e32 v3, 0xffff0000, v200
	v_pk_mul_f32 v[0:1], v[0:1], v[2:3]
	v_pk_mul_f32 v[2:3], v[44:45], v[4:5] op_sel_hi:[1,0]
	v_pk_mul_f32 v[2:3], v[108:109], v[2:3]
	v_lshlrev_b32_e32 v76, 16, v201
	v_and_b32_e32 v77, 0xffff0000, v201
	v_pk_mul_f32 v[2:3], v[2:3], v[76:77]
	v_cvt_pk_bf16_f32 v0, v0, v1
	v_cvt_pk_bf16_f32 v1, v2, v3
	global_store_dwordx2 v[6:7], v[0:1], off offset:224
	s_waitcnt vmcnt(22)
	v_pk_mul_f32 v[0:1], v[110:111], v[38:39]
	v_lshlrev_b32_e32 v2, 16, v202
	v_and_b32_e32 v3, 0xffff0000, v202
	v_pk_mul_f32 v[0:1], v[0:1], v[2:3]
	v_pk_mul_f32 v[2:3], v[40:41], v[4:5] op_sel_hi:[1,0]
	v_pk_mul_f32 v[2:3], v[112:113], v[2:3]
	v_lshlrev_b32_e32 v76, 16, v203
	v_and_b32_e32 v77, 0xffff0000, v203
	v_pk_mul_f32 v[2:3], v[2:3], v[76:77]
	v_cvt_pk_bf16_f32 v0, v0, v1
	v_cvt_pk_bf16_f32 v1, v2, v3
	global_store_dwordx2 v[6:7], v[0:1], off offset:256
	s_waitcnt vmcnt(21)
	v_pk_mul_f32 v[0:1], v[114:115], v[34:35]
	v_lshlrev_b32_e32 v2, 16, v204
	v_and_b32_e32 v3, 0xffff0000, v204
	v_pk_mul_f32 v[0:1], v[0:1], v[2:3]
	v_pk_mul_f32 v[2:3], v[36:37], v[4:5] op_sel_hi:[1,0]
	v_pk_mul_f32 v[2:3], v[116:117], v[2:3]
	v_lshlrev_b32_e32 v76, 16, v205
	v_and_b32_e32 v77, 0xffff0000, v205
	v_pk_mul_f32 v[2:3], v[2:3], v[76:77]
	v_cvt_pk_bf16_f32 v0, v0, v1
	v_cvt_pk_bf16_f32 v1, v2, v3
	global_store_dwordx2 v[6:7], v[0:1], off offset:288
	s_waitcnt vmcnt(20)
	v_pk_mul_f32 v[0:1], v[118:119], v[30:31]
	v_lshlrev_b32_e32 v2, 16, v206
	v_and_b32_e32 v3, 0xffff0000, v206
	v_pk_mul_f32 v[0:1], v[0:1], v[2:3]
	v_pk_mul_f32 v[2:3], v[32:33], v[4:5] op_sel_hi:[1,0]
	v_pk_mul_f32 v[2:3], v[120:121], v[2:3]
	v_lshlrev_b32_e32 v76, 16, v207
	v_and_b32_e32 v77, 0xffff0000, v207
	v_pk_mul_f32 v[2:3], v[2:3], v[76:77]
	v_cvt_pk_bf16_f32 v0, v0, v1
	v_cvt_pk_bf16_f32 v1, v2, v3
	global_store_dwordx2 v[6:7], v[0:1], off offset:320
	s_waitcnt vmcnt(19)
	v_pk_mul_f32 v[0:1], v[122:123], v[26:27]
	v_lshlrev_b32_e32 v2, 16, v208
	v_and_b32_e32 v3, 0xffff0000, v208
	v_pk_mul_f32 v[0:1], v[0:1], v[2:3]
	v_pk_mul_f32 v[2:3], v[28:29], v[4:5] op_sel_hi:[1,0]
	v_pk_mul_f32 v[2:3], v[124:125], v[2:3]
	v_lshlrev_b32_e32 v76, 16, v209
	v_and_b32_e32 v77, 0xffff0000, v209
	v_pk_mul_f32 v[2:3], v[2:3], v[76:77]
	v_cvt_pk_bf16_f32 v0, v0, v1
	v_cvt_pk_bf16_f32 v1, v2, v3
	global_store_dwordx2 v[6:7], v[0:1], off offset:352
	s_waitcnt vmcnt(18)
	v_pk_mul_f32 v[0:1], v[126:127], v[22:23]
	v_lshlrev_b32_e32 v2, 16, v210
	v_and_b32_e32 v3, 0xffff0000, v210
	v_pk_mul_f32 v[0:1], v[0:1], v[2:3]
	v_pk_mul_f32 v[2:3], v[24:25], v[4:5] op_sel_hi:[1,0]
	v_pk_mul_f32 v[2:3], v[128:129], v[2:3]
	v_lshlrev_b32_e32 v76, 16, v211
	v_and_b32_e32 v77, 0xffff0000, v211
	v_pk_mul_f32 v[2:3], v[2:3], v[76:77]
	v_cvt_pk_bf16_f32 v0, v0, v1
	v_cvt_pk_bf16_f32 v1, v2, v3
	global_store_dwordx2 v[6:7], v[0:1], off offset:384
	s_waitcnt vmcnt(17)
	v_pk_mul_f32 v[0:1], v[130:131], v[18:19]
	v_lshlrev_b32_e32 v2, 16, v212
	v_and_b32_e32 v3, 0xffff0000, v212
	v_pk_mul_f32 v[0:1], v[0:1], v[2:3]
	v_pk_mul_f32 v[2:3], v[20:21], v[4:5] op_sel_hi:[1,0]
	v_pk_mul_f32 v[2:3], v[132:133], v[2:3]
	v_lshlrev_b32_e32 v76, 16, v213
	v_and_b32_e32 v77, 0xffff0000, v213
	v_pk_mul_f32 v[2:3], v[2:3], v[76:77]
	v_cvt_pk_bf16_f32 v0, v0, v1
	v_cvt_pk_bf16_f32 v1, v2, v3
	global_store_dwordx2 v[6:7], v[0:1], off offset:416
	s_waitcnt vmcnt(16)
	v_pk_mul_f32 v[0:1], v[134:135], v[14:15]
	v_lshlrev_b32_e32 v2, 16, v214
	v_and_b32_e32 v3, 0xffff0000, v214
	v_pk_mul_f32 v[0:1], v[0:1], v[2:3]
	v_pk_mul_f32 v[2:3], v[16:17], v[4:5] op_sel_hi:[1,0]
	v_pk_mul_f32 v[2:3], v[136:137], v[2:3]
	v_lshlrev_b32_e32 v76, 16, v215
	v_and_b32_e32 v77, 0xffff0000, v215
	v_pk_mul_f32 v[2:3], v[2:3], v[76:77]
	v_cvt_pk_bf16_f32 v0, v0, v1
	v_cvt_pk_bf16_f32 v1, v2, v3
	global_store_dwordx2 v[6:7], v[0:1], off offset:448
	s_waitcnt vmcnt(15)
	v_pk_mul_f32 v[0:1], v[138:139], v[10:11]
	v_lshlrev_b32_e32 v2, 16, v216
	v_and_b32_e32 v3, 0xffff0000, v216
	v_pk_mul_f32 v[0:1], v[0:1], v[2:3]
	v_pk_mul_f32 v[2:3], v[12:13], v[4:5] op_sel_hi:[1,0]
	v_pk_mul_f32 v[2:3], v[140:141], v[2:3]
	v_lshlrev_b32_e32 v76, 16, v217
	v_and_b32_e32 v77, 0xffff0000, v217
	v_pk_mul_f32 v[2:3], v[2:3], v[76:77]
	v_cvt_pk_bf16_f32 v0, v0, v1
	v_cvt_pk_bf16_f32 v1, v2, v3
	global_store_dwordx2 v[6:7], v[0:1], off offset:480
	s_cbranch_vccnz .LBB0_858
